# scan: each (batch,head) recurrence split over two workgroups (64 state columns each; waves 4-7 only stage the chunk image)
# speedup vs baseline: 1.0095x; 1.0095x over previous
; #define LAS __attribute__((address_space(3)))
; DI void scan_phase(LAS unsigned char* lds, const Args& a, int l) {
;     int tid_ = threadIdx.x; asm volatile("" : "+v"(tid_));
;     const int tid = tid_, s = tid >> 6, lane = tid & 63, fr = lane & 15, fq = lane >> 4;
;     constexpr int BUF = 62464, O_WK = 0, O_QD = 17408, O_KET = 34816, O_QK = 53248;
;     const int lw0 = (tid >> 4) * 272 + (tid & 15) * 16, lw1 = ((tid + 512) >> 4) * 272 + (tid & 15) * 16;
;     const int lk0 = (tid >> 3) * 144 + (tid & 7) * 16, lk1 = ((tid + 512) >> 3) * 144 + (tid & 7) * 16;
;     ...
;     for (int bh = blockIdx.x; bh < 32; bh += gridDim.x) {
;         const int b = bh >> 2, h = bh & 3;
;         const size_t item0 = (size_t)bh * 32;
.LBB0_100:
	s_cmp_gt_i32 s5, 2
	s_mov_b64 s[8:9], -1
	s_cbranch_scc0 .LBB0_738
	s_cmp_lt_i32 s5, 4
	s_cbranch_scc1 .LBB0_487
	s_cmp_gt_i32 s5, 4
	s_cbranch_scc0 .LBB0_219
	s_cmp_lt_u32 s4, 64
	s_cbranch_scc0 .LBB0_112
	v_readlane_b32 s8, v253, 52
	v_readlane_b32 s9, v253, 53
	s_waitcnt vmcnt(0)
	v_mov_b32_e32 v0, v152
	v_lshlrev_b32_e32 v108, 4, v0
	v_lshrrev_b32_e32 v1, 4, v0
	v_and_b32_e32 v2, 0xf0, v108
	v_mad_u64_u32 v[110:111], s[8:9], v1, s47, v[2:3]
	v_add_u32_e32 v1, 0x200, v0
	v_lshrrev_b32_e32 v3, 4, v1
	v_mad_u64_u32 v[112:113], s[8:9], v3, s47, v[2:3]
	v_lshrrev_b32_e32 v3, 3, v0
	v_and_b32_e32 v2, 0x70, v108
	s_movk_i32 s2, 0x120
	v_lshrrev_b32_e32 v1, 3, v1
	v_mad_u64_u32 v[114:115], s[8:9], v3, s2, v[2:3]
	v_mad_u64_u32 v[116:117], s[8:9], v1, s2, v[2:3]
	v_add_u32_e32 v116, 0x90, v114
	v_lshrrev_b32_e32 v151, 8, v0
	v_mul_u32_u24_e32 v151, 0x2370, v151
	v_sub_u32_e32 v151, v114, v151
	v_readlane_b32 s8, v253, 56
	v_ashrrev_i32_e32 v109, 31, v108
	v_readlane_b32 s9, v253, 57
	v_ashrrev_i32_e32 v1, 6, v0
	s_and_b32 s2, s4, 1
	v_readfirstlane_b32 s101, v1
	s_lshl_b32 s2, s2, 2
	v_and_b32_e32 v1, 3, v1
	s_lshr_b32 s101, s101, 2
	v_or_b32_e32 v1, s2, v1
	v_lshlrev_b32_e32 v2, 10, v1
	v_lshl_add_u64 v[118:119], s[8:9], 0, v[108:109]
	v_readlane_b32 s8, v253, 58
	v_readlane_b32 s9, v253, 59
	v_and_b32_e32 v4, 48, v0
	v_readlane_b32 s2, v254, 59
	v_lshl_add_u64 v[120:121], s[8:9], 0, v[108:109]
	v_readlane_b32 s8, v253, 60
	v_readlane_b32 s9, v253, 61
	v_ashrrev_i32_e32 v3, 31, v2
	v_add_u32_e32 v12, s2, v4
	v_lshl_add_u64 v[122:123], s[8:9], 0, v[108:109]
	v_readlane_b32 s8, v253, 62
	v_readlane_b32 s9, v253, 63
	v_readlane_b32 s2, v254, 60
	v_and_b32_e32 v6, 15, v0
	v_lshl_add_u64 v[124:125], s[8:9], 0, v[108:109]
	v_readlane_b32 s8, v254, 0
	v_and_b32_e32 v7, 63, v0
	v_bfe_u32 v8, v0, 4, 2
	v_lshlrev_b32_e32 v0, 4, v1
	v_mov_b32_e32 v5, 0x1100
	v_add_u32_e32 v13, s2, v4
	v_readlane_b32 s2, v254, 61
	v_lshlrev_b64 v[2:3], 2, v[2:3]
	v_readlane_b32 s9, v254, 1
	v_ashrrev_i32_e32 v1, 31, v0
	v_add_u32_e32 v113, 0, v4
	v_mad_u32_u24 v9, v6, s47, v5
	v_add_u32_e32 v14, s2, v4
	v_lshl_add_u64 v[4:5], s[8:9], 0, v[2:3]
	v_readlane_b32 s8, v253, 50
	v_lshlrev_b32_e32 v128, 4, v7
	v_lshlrev_b64 v[0:1], 2, v[0:1]
	v_readlane_b32 s9, v253, 51
	v_mul_u32_u24_e32 v115, 0x110, v6
	v_mad_u32_u24 v10, v6, s47, v252
	v_mad_u32_u24 v11, v6, s47, v161
	v_mul_u32_u24_e32 v117, 0x120, v6
	v_lshl_add_u64 v[126:127], v[4:5], 0, v[128:129]
	v_lshl_add_u64 v[4:5], s[8:9], 0, v[0:1]
	v_lshlrev_b32_e32 v6, 2, v6
	v_mov_b32_e32 v7, v129
	v_readlane_b32 s8, v254, 4
	v_lshl_add_u64 v[132:133], v[4:5], 0, v[6:7]
	v_lshlrev_b32_e32 v4, 11, v8
	v_mov_b32_e32 v5, v129
	v_readlane_b32 s9, v254, 5
	v_or_b32_e32 v2, v2, v128
	v_lshlrev_b32_e32 v111, 2, v8
	v_lshl_add_u64 v[4:5], s[8:9], 0, v[4:5]
	s_mov_b64 s[8:9], 0x1ece6000
	v_lshl_add_u64 v[0:1], v[4:5], 0, v[0:1]
	v_lshl_add_u64 v[136:137], v[108:109], 0, s[8:9]
	s_mov_b64 s[8:9], 0x19cea800
	s_lshl_b32 s14, s25, 5
	v_lshl_add_u64 v[134:135], v[0:1], 0, v[6:7]
	v_lshl_add_u64 v[138:139], v[2:3], 0, s[8:9]
	v_add_u32_e32 v131, v113, v9
	v_add_u32_e32 v178, v113, v11
	v_add_u32_e32 v179, v12, v115
	v_add_u32_e32 v180, v13, v117
	v_add_u32_e32 v181, v14, v117
	s_lshr_b32 s8, s4, 1
	s_lshl_b32 s15, s8, 9
	s_branch .LBB0_107

; #define LAS __attribute__((address_space(3)))
; #define MFMA16(a, b, c) __builtin_amdgcn_mfma_f32_16x16x32_bf16((a), (b), (c), 0, 0, 0)
; #define SC_LOADUV(it_) do { const float* _u = (const float*)(a.ws + WS_UV) + (size_t)(it_) * 8192 + s * 1024 + lane * 4; \
;         uvn[0] = *(const f32x4*)_u; uvn[1] = *(const f32x4*)(_u + 256); uvn[2] = *(const f32x4*)(_u + 512); uvn[3] = *(const f32x4*)(_u + 768); \
;         gen = ((const float*)(a.ws + WS_GE))[(it_)]; } while (0)
; #define SC_STORE(bo_) do { LAS unsigned char* _b = lds + (bo_); \
;         *(LAS u32x4*)(_b + O_WK + lw0) = pf[0]; *(LAS u32x4*)(_b + O_WK + lw1) = pf[1]; *(LAS u32x4*)(_b + O_QD + lw0) = pf[2]; *(LAS u32x4*)(_b + O_QD + lw1) = pf[3]; \
;         *(LAS u32x4*)(_b + O_KET + lk0) = pf[4]; *(LAS u32x4*)(_b + O_KET + lk1) = pf[5]; *(LAS u32x4*)(_b + O_QK + lk0) = pf[6]; } while (0)
; DI void scan_phase(LAS unsigned char* lds, const Args& a, int l) {
;     ...
;         for (int n = 0; n < 32; ++n) {
;             const int cur = (n & 1) * BUF;
;             if (n + 1 < 32) { SC_STORE(BUF - cur); SC_LOADUV(item0 + n + 1); }
;             if (n + 2 < 32) SC_LOADG(item0 + n + 2);
;             const LAS unsigned char* B = lds + cur;
;             f32x4 ws[4], o[4];
; #pragma unroll
;             for (int m = 0; m < 4; ++m) { ws[m] = (f32x4){0.f, 0.f, 0.f, 0.f}; o[m] = (f32x4){0.f, 0.f, 0.f, 0.f}; }
; #pragma unroll
;             for (int ks = 0; ks < 4; ++ks)
; #pragma unroll
;                 for (int m = 0; m < 4; ++m) { const bf16x8 av = *(const LAS bf16x8*)(B + O_WK + (16 * m + fr) * 272 + (32 * ks + 8 * fq) * 2); ws[m] = MFMA16(av, Sb[ks], ws[m]); }
.LBB0_108:
	s_cmp_lg_u32 s101, 0
	s_cbranch_scc1 .Lscan_idle
	s_bitcmp1_b32 s9, 0
	s_cselect_b32 s2, 0xf400, 0
	v_add3_u32 v250, s2, v113, v115
	v_add3_u32 v251, s2, v113, v117
	ds_read_b128 v[214:217], v250
	ds_read_b128 v[218:221], v250 offset:4352
	ds_read_b128 v[222:225], v250 offset:8704
	ds_read_b128 v[226:229], v250 offset:13056
	ds_read_b128 v[230:233], v250 offset:64
	ds_read_b128 v[234:237], v250 offset:4416
	ds_read_b128 v[238:241], v250 offset:8768
	s_cmp_eq_u32 s9, 31
	s_cbranch_scc1 .Lscan_nostage
	s_sub_i32 s10, 0, s2
	v_add_u32_e32 v32, s10, v110
	s_add_i32 s11, s10, 0xf400
	ds_write_b128 v32, v[48:51] offset:62464
	v_add_u32_e32 v33, s10, v112
	ds_write_b128 v33, v[52:55] offset:62464
	v_add_u32_e32 v32, s11, v110
	ds_write_b128 v32, v[56:59] offset:17408
	v_add_u32_e32 v33, s11, v112
	ds_write_b128 v33, v[60:63] offset:17408
	v_add_u32_e32 v32, s11, v114
	v_add_u32_e32 v33, s11, v116
	ds_write_b128 v32, v[64:67] offset:34816
	ds_write_b128 v33, v[68:71] offset:34816
	v_add_u32_e32 v32, s11, v151
	ds_write_b128 v32, v[72:75] offset:53248

; #define SC_LOADUV(it_) do { const float* _u = (const float*)(a.ws + WS_UV) + (size_t)(it_) * 8192 + s * 1024 + lane * 4; \
;         uvn[0] = *(const f32x4*)_u; uvn[1] = *(const f32x4*)(_u + 256); uvn[2] = *(const f32x4*)(_u + 512); uvn[3] = *(const f32x4*)(_u + 768); \
;         gen = ((const float*)(a.ws + WS_GE))[(it_)]; } while (0)
; #define SC_STORE(bo_) do { LAS unsigned char* _b = lds + (bo_); \
;         *(LAS u32x4*)(_b + O_WK + lw0) = pf[0]; *(LAS u32x4*)(_b + O_WK + lw1) = pf[1]; *(LAS u32x4*)(_b + O_QD + lw0) = pf[2]; *(LAS u32x4*)(_b + O_QD + lw1) = pf[3]; \
;         *(LAS u32x4*)(_b + O_KET + lk0) = pf[4]; *(LAS u32x4*)(_b + O_KET + lk1) = pf[5]; *(LAS u32x4*)(_b + O_QK + lk0) = pf[6]; } while (0)
; DI void scan_phase(LAS unsigned char* lds, const Args& a, int l) {
;     ...
;         for (int n = 0; n < 32; ++n) {
;             const int cur = (n & 1) * BUF;
;             if (n + 1 < 32) { SC_STORE(BUF - cur); SC_LOADUV(item0 + n + 1); }
;             if (n + 2 < 32) SC_LOADG(item0 + n + 2);
;     ...
;             __syncthreads();
.Lscan_idle:
	s_bitcmp1_b32 s9, 0
	s_cselect_b32 s2, 0xf400, 0
	s_cmp_eq_u32 s9, 31
	s_cbranch_scc1 .Lscan_idle_nostage
	s_sub_i32 s10, 0, s2
	v_add_u32_e32 v32, s10, v110
	s_add_i32 s11, s10, 0xf400
	ds_write_b128 v32, v[48:51] offset:62464
	v_add_u32_e32 v33, s10, v112
	ds_write_b128 v33, v[52:55] offset:62464
	v_add_u32_e32 v32, s11, v110
	ds_write_b128 v32, v[56:59] offset:17408
	v_add_u32_e32 v33, s11, v112
	ds_write_b128 v33, v[60:63] offset:17408
	v_add_u32_e32 v32, s11, v114
	v_add_u32_e32 v33, s11, v116
	ds_write_b128 v32, v[64:67] offset:34816
	ds_write_b128 v33, v[68:71] offset:34816
	v_add_u32_e32 v32, s11, v151
	ds_write_b128 v32, v[72:75] offset:53248
.Lscan_idle_nostage:
	s_cmp_gt_u32 s9, 29
	s_cbranch_scc1 .Lscan_idle_noG
	v_lshl_add_u64 v[64:65], s[22:23], 0, v[146:147]
	v_add_co_u32_e32 v48, vcc, 0x1bcea000, v64
	v_lshl_add_u64 v[72:73], s[22:23], 0, v[144:145]
	s_nop 0
	v_addc_co_u32_e32 v49, vcc, 0, v65, vcc
	v_add_co_u32_e32 v52, vcc, 0x1bcec000, v64
	s_nop 1
	v_addc_co_u32_e32 v53, vcc, 0, v65, vcc
	v_add_co_u32_e32 v56, vcc, 0x1ccea000, v64
	global_load_dwordx4 v[48:51], v[48:49], off
	s_nop 0
	global_load_dwordx4 v[52:55], v[52:53], off
	v_addc_co_u32_e32 v57, vcc, 0, v65, vcc
	v_add_co_u32_e32 v60, vcc, 0x1ccec000, v64
	s_nop 1
	v_addc_co_u32_e32 v61, vcc, 0, v65, vcc
	v_add_co_u32_e32 v66, vcc, 0x1dcea000, v64
	global_load_dwordx4 v[56:59], v[56:57], off
	s_nop 0
	global_load_dwordx4 v[60:63], v[60:61], off
	v_addc_co_u32_e32 v67, vcc, 0, v65, vcc
	v_add_co_u32_e32 v68, vcc, 0x1dcec000, v64
	s_nop 1
	v_addc_co_u32_e32 v69, vcc, 0, v65, vcc
	global_load_dwordx4 v[64:67], v[66:67], off
	s_nop 0
	global_load_dwordx4 v[68:71], v[68:69], off
	s_nop 0
	global_load_dwordx4 v[72:75], v[72:73], off
.Lscan_idle_noG:
	s_mov_b64 s[10:11], 0x4000
	v_lshl_add_u64 v[146:147], v[146:147], 0, s[10:11]
	v_lshl_add_u64 v[144:145], v[144:145], 0, s[26:27]
	s_add_i32 s9, s9, 1
	s_waitcnt lgkmcnt(0)
	s_cmp_eq_u32 s9, 32
	s_barrier
	s_cbranch_scc1 .LBB0_112
	s_waitcnt vmcnt(0)
	s_branch .Lscan_idle

; __global__ void __launch_bounds__(512) mk_fwd(Args a) {
;     ...
;             if ((int)blockIdx.x >= 32 || G <= 32) {
;                 const int nb = (G > 32) ? G - 32 : G, b0 = (G > 32) ? (int)blockIdx.x - 32 : (int)blockIdx.x;
;                 for (int it = b0; it < 512 + 516; it += nb) {
;                     if (PHON(6) && it < 512) sample_item(lds, a, l, it);
;                     else if (PHON(7) && it >= 512) pool_item(lds, a, l, it - 512);
;                 }
.LBB0_114:
	s_cmp_ge_u32 s4, 64
	s_cbranch_scc0 .LBB0_218
	v_readlane_b32 s2, v255, 5
	s_add_u32 s2, s2, 0x2800000
	v_readlane_b32 s8, v255, 6
	s_addc_u32 s28, s8, 0
	s_lshl_b32 s29, s25, 7
	s_lshl_b32 s10, s25, 9
	s_add_i32 s34, s29, 0xffffc000
	s_ashr_i32 s11, s10, 31
	s_sub_i32 s35, s4, 64
	v_readlane_b32 s8, v254, 8
	s_add_i32 s8, s8, -36
	s_cmp_ge_i32 s35, s8
	s_cbranch_scc0 .Litems_regular
	s_sub_i32 s35, s35, s8
	s_addk_i32 s35, 0x400

; __global__ void __launch_bounds__(512) mk_fwd(Args a) {
;     ...
;                 for (int it = b0; it < 512 + 516; it += nb) {
;                     if (PHON(6) && it < 512) sample_item(lds, a, l, it);
;                     else if (PHON(7) && it >= 512) pool_item(lds, a, l, it - 512);
;                 }
.LBB0_117:
	v_readlane_b32 s8, v254, 8
	s_add_i32 s8, s8, -36
	s_add_i32 s35, s35, s8
	s_cmpk_gt_i32 s35, 0x3ff
	s_waitcnt vmcnt(63) expcnt(7) lgkmcnt(15)
	s_cbranch_scc1 .LBB0_218
